# phase 4: half the workgroups run the GLA scan before attention (spreads memory traffic); GLA loop LDS reads hoisted
# baseline (speedup 1.0000x reference)
; #define LAS __attribute__((address_space(3)))
; #define RUN_PH(ph) if ((ph) == ONLY_PH && P.ph_lo <= (ph) && (ph) < P.ph_hi)
; #define RUN_PH(ph) if (P.ph_lo <= (ph) && (ph) < P.ph_hi)
; __device__ __forceinline__ void attn_item(const Params& P, int item, LAS unsigned char* lds, float mfix2) {
;     const int tid = threadIdx.x, lane = tid & 63, wave = __builtin_amdgcn_readfirstlane(tid >> 6), r16 = lane & 15, q4 = lane >> 4;
;     const int hp = item & 1, qb = (item >> 1) & 15, kvh = (item >> 5) & 1, b = item >> 6;
;     const int head = kvh * 4 + hp * 2 + (wave >> 2), rw0 = (wave & 3) * 32, q0 = qb * 128;
;     const bf16_t* Kb = (const bf16_t*)(P.ws + WS_KP) + (size_t)(b * 2 + kvh) * KVLEN * 128;
;     const bf16_t* Vtb = (const bf16_t*)(P.ws + WS_VTA) + (size_t)(b * 2 + kvh) * 128 * KVLEN;
;     bf16_t* mix = (bf16_t*)(P.ws + WS_MIX);
;     LAS unsigned char* Pw = lds + 71680 + wave * 4608;
;     bf16x8 qf[2][4];
;     { const bf16_t* qbase = (const bf16_t*)(P.ws + WS_QP) + ((size_t)(b * 8 + head) * SEQ + q0 + rw0) * 128;
; #pragma unroll
;       for (int rb = 0; rb < 2; ++rb)
; #pragma unroll
;           for (int ks = 0; ks < 4; ++ks) qf[rb][ks] = *(const bf16x8*)(qbase + (rb * 16 + r16) * 128 + ks * 32 + q4 * 8); }
;     const float psink = exp2f(P.in[13][head] * LOG2E - mfix2);
;     f32x4 o[2][8]; float lsum[2][4];
; #pragma unroll
;     for (int rb = 0; rb < 2; ++rb) {
; #pragma unroll
;         for (int db = 0; db < 8; ++db) o[rb][db] = (f32x4){0.f, 0.f, 0.f, 0.f};
; #pragma unroll
;         for (int j = 0; j < 4; ++j) lsum[rb][j] = 0.f; }
;     const int lt_first = qb == 0 ? 0 : (qb - 1) * 2, lt_last = (qb * 2 + 3) > 31 ? 31 : (qb * 2 + 3), ntiles = 4 + lt_last - lt_first + 1;
;     const int kkey0 = tid >> 4, kseg = tid & 15, vdim0 = tid >> 3, vseg = tid & 7;
; __global__ void __launch_bounds__(512, 2) mega(Params P) {
;     ...
;     RUN_PH(4) {
;         float gq = fmaxf(fabsf(P.in[11][threadIdx.x & 63]), fabsf(P.in[11][64 + (threadIdx.x & 63)])), gk = fmaxf(fabsf(P.in[12][threadIdx.x & 63]), fabsf(P.in[12][64 + (threadIdx.x & 63)]));
; #pragma unroll
;         for (int o = 1; o < 64; o <<= 1) { gq = fmaxf(gq, __shfl_xor(gq, o)); gk = fmaxf(gk, __shfl_xor(gk, o)); }
;         const float mfix2 = 11.313708498984761f * gq * gk * LOG2E;
;         for (int it = blockIdx.x; it < 512; it += gridDim.x) attn_item(P, it, lds, mfix2);
.LBB0_531:
	s_add_u32 s36, s50, 0xb418000
	s_addc_u32 s37, s51, 0
	s_add_u32 s38, s50, 0x17c18000
	s_addc_u32 s39, s51, 0
	s_cmp_lt_i32 s24, 5
	s_cselect_b64 s[42:43], -1, 0
	s_and_b64 s[0:1], s[42:43], s[0:1]
	s_andn2_b64 vcc, exec, s[0:1]
	s_cbranch_vccnz .LBB0_571
	s_mov_b32 s100, 0
	s_bitcmp1_b32 s22, 7
	s_cbranch_scc0 .Lp4_att
	s_mov_b32 s100, 1
	s_branch .LBB0_553
.Lp4_att:
	v_and_b32_e32 v0, 63, v224
	v_lshlrev_b32_e32 v1, 2, v0
	global_load_dword v2, v1, s[74:75] offset:256
	global_load_dword v3, v1, s[74:75]
	global_load_dword v4, v1, s[76:77] offset:256
	global_load_dword v5, v1, s[76:77]
	v_mbcnt_lo_u32_b32 v1, -1, 0
	v_mbcnt_hi_u32_b32 v1, -1, v1
	v_and_b32_e32 v6, 64, v1
	v_xor_b32_e32 v7, 1, v1
	v_add_u32_e32 v6, 64, v6
	v_cmp_lt_i32_e32 vcc, v7, v6
	v_xor_b32_e32 v8, 2, v1
	v_xor_b32_e32 v9, 4, v1
	v_cndmask_b32_e32 v7, v1, v7, vcc
	v_lshlrev_b32_e32 v178, 2, v7
	v_cmp_lt_i32_e32 vcc, v8, v6
	v_xor_b32_e32 v10, 8, v1
	v_xor_b32_e32 v11, 16, v1
	v_cndmask_b32_e32 v7, v1, v8, vcc
	v_lshlrev_b32_e32 v179, 2, v7
	v_cmp_lt_i32_e32 vcc, v9, v6
	v_xor_b32_e32 v12, 32, v1
	s_mov_b32 s1, 0
	v_cndmask_b32_e32 v7, v1, v9, vcc
	v_lshlrev_b32_e32 v180, 2, v7
	v_cmp_lt_i32_e32 vcc, v10, v6
	s_cmpk_gt_i32 s22, 0x1ff
	v_and_b32_e32 v181, 7, v224
	v_cndmask_b32_e32 v7, v1, v10, vcc
	v_lshlrev_b32_e32 v182, 2, v7
	v_cmp_lt_i32_e32 vcc, v11, v6
	s_waitcnt vmcnt(0)
	v_max_f32_e64 v2, |v2|, |v2|
	v_max_f32_e64 v3, |v3|, |v3|
	v_max_f32_e64 v4, |v4|, |v4|
	v_max_f32_e64 v5, |v5|, |v5|
	v_max_f32_e32 v2, v3, v2
	v_max_f32_e32 v3, v5, v4
	ds_bpermute_b32 v4, v178, v2
	ds_bpermute_b32 v5, v178, v3
	v_cndmask_b32_e32 v7, v1, v11, vcc
	v_lshlrev_b32_e32 v7, 2, v7
	v_cmp_lt_i32_e32 vcc, v12, v6
	s_waitcnt lgkmcnt(1)
	v_max_f32_e32 v4, v4, v4
	s_waitcnt lgkmcnt(0)
	v_max_f32_e32 v5, v5, v5
	v_max_f32_e32 v2, v2, v4
	v_max_f32_e32 v3, v3, v5
	ds_bpermute_b32 v4, v179, v2
	ds_bpermute_b32 v5, v179, v3
	v_cndmask_b32_e32 v1, v1, v12, vcc
	v_lshlrev_b32_e32 v6, 2, v1
	s_waitcnt lgkmcnt(1)
	v_max_f32_e32 v4, v4, v4
	s_waitcnt lgkmcnt(0)
	v_max_f32_e32 v5, v5, v5
	v_max_f32_e32 v2, v2, v4
	v_max_f32_e32 v3, v3, v5
	ds_bpermute_b32 v4, v180, v2
	ds_bpermute_b32 v5, v180, v3
	s_waitcnt lgkmcnt(1)
	v_max_f32_e32 v4, v4, v4
	s_waitcnt lgkmcnt(0)
	v_max_f32_e32 v5, v5, v5
	v_max_f32_e32 v2, v2, v4
	v_max_f32_e32 v3, v3, v5
	ds_bpermute_b32 v4, v182, v2
	ds_bpermute_b32 v5, v182, v3
	s_waitcnt lgkmcnt(1)
	v_max_f32_e32 v4, v4, v4
	s_waitcnt lgkmcnt(0)
	v_max_f32_e32 v5, v5, v5
	v_max_f32_e32 v2, v2, v4
	v_max_f32_e32 v3, v3, v5
	ds_bpermute_b32 v4, v7, v2
	ds_bpermute_b32 v5, v7, v3
	s_waitcnt lgkmcnt(1)
	v_max_f32_e32 v1, v4, v4
	s_waitcnt lgkmcnt(0)
	v_max_f32_e32 v4, v5, v5
	v_max_f32_e32 v2, v2, v1
	v_max_f32_e32 v1, v3, v4
	ds_bpermute_b32 v4, v6, v2
	ds_bpermute_b32 v3, v6, v1
	s_cbranch_scc1 .LBB0_553
	s_waitcnt lgkmcnt(1)
	v_max_f32_e32 v4, v4, v4
	v_max_f32_e32 v2, v2, v2
	v_max_f32_e32 v2, v2, v4
	s_waitcnt lgkmcnt(0)
	v_max_f32_e32 v3, v3, v3
	v_max_f32_e32 v1, v1, v1
	v_max_f32_e32 v1, v1, v3
	v_mul_f32_e32 v2, 0x413504f3, v2
	v_mul_f32_e32 v1, v1, v2
	v_and_b32_e32 v3, 15, v224
	v_and_b32_e32 v156, 48, v0
	v_mov_b32_e32 v157, 0
	v_mul_f32_e32 v183, 0x3fb8aa3b, v1
	v_lshrrev_b32_e32 v184, 4, v0
	v_lshl_add_u64 v[0:1], s[50:51], 0, v[156:157]
	v_lshlrev_b32_e32 v156, 8, v3
	v_lshl_add_u64 v[0:1], v[0:1], 0, v[156:157]
	s_mov_b64 s[2:3], 0x26718000
	v_lshlrev_b32_e32 v8, 2, v184
	v_lshl_add_u64 v[158:159], v[0:1], 0, s[2:3]
	v_lshrrev_b32_e32 v185, 4, v224
	v_lshrrev_b32_e32 v1, 3, v224
	s_movk_i32 s0, 0x110
	v_sub_u32_e32 v8, v8, v3
	v_mul_u32_u24_e32 v5, 0x900, v1
	v_mad_u32_u24 v7, v185, s0, 0
	s_movk_i32 s0, 0x90
	v_add_u32_e32 v189, 0xffffff7f, v8
	v_mov_b32_e32 v8, 0x3600
	v_lshlrev_b32_e32 v0, 7, v185
	v_and_b32_e32 v186, 48, v224
	v_mad_u32_u24 v12, v3, s0, v8
	v_mov_b32_e32 v8, 0x3f00
	v_lshlrev_b32_e32 v156, 1, v5
	s_add_u32 s15, s50, 0x28718000
	v_lshlrev_b32_e32 v2, 3, v3
	v_add_u32_e32 v4, 0x1000, v0
	v_lshlrev_b32_e32 v6, 3, v181
	v_lshlrev_b32_e32 v160, 4, v3
	v_mad_u32_u24 v1, v1, s0, 0
	v_lshlrev_b32_e32 v10, 4, v181
	v_add_u32_e32 v187, 0, v186
	v_lshlrev_b32_e32 v188, 1, v3
	v_mul_u32_u24_e32 v11, 0x110, v3
	v_mul_u32_u24_e32 v191, 0x90, v3
	v_mad_u32_u24 v3, v3, s0, v8
	v_mov_b32_e32 v161, v157
	v_lshl_add_u64 v[8:9], s[50:51], 0, v[156:157]
	s_mov_b64 s[2:3], 0x29018000
	s_mov_b32 s14, 0x3fb8aa3b
	s_addc_u32 s16, s51, 0
	s_movk_i32 s17, 0x1000
	v_mul_u32_u24_e32 v190, 0x240, v184
	v_lshl_add_u64 v[162:163], s[38:39], 0, v[160:161]
	v_mul_u32_u24_e32 v161, 0x110, v184
	v_or_b32_e32 v192, 4, v184
	v_or_b32_e32 v193, 8, v184
	v_or_b32_e32 v194, 12, v184
	v_or_b32_e32 v195, 16, v184
	v_or_b32_e32 v196, 20, v184
	v_or_b32_e32 v197, 24, v184
	v_or_b32_e32 v198, 28, v184
	v_mul_u32_u24_e32 v199, 0x440, v184
	v_lshl_add_u64 v[164:165], v[8:9], 0, s[2:3]
	v_lshlrev_b32_e32 v166, 1, v0
	v_lshlrev_b32_e32 v156, 1, v2
	v_lshlrev_b32_e32 v168, 1, v4
	v_lshlrev_b32_e32 v170, 1, v6
	s_mov_b64 s[2:3], 0x48000
	s_mov_b32 s18, 0x48000
	s_mov_b32 s19, 0xc2fc0000
	s_movk_i32 s28, 0xfeff
	v_add_u32_e32 v200, v187, v12
	v_add_u32_e32 v201, v187, v3
	v_mov_b32_e32 v202, 0x90000
	v_add_u32_e32 v203, v7, v160
	v_add_u32_e32 v204, v1, v10
	v_add_u32_e32 v205, v187, v11
	v_mov_b32_e32 v206, 0x42800000
	v_not_b32_e32 v207, 63
	s_mov_b32 s29, s22
	s_branch .LBB0_536

; #define LAS __attribute__((address_space(3)))
; __device__ __forceinline__ void gla_scan_item(const Params& P, int item, LAS unsigned char* lds) {
;     const int tid = threadIdx.x, lane = tid & 63, wave = __builtin_amdgcn_readfirstlane(tid >> 6), r16 = lane & 15, q4 = lane >> 4;
;     const int es = item & 3, h = (item >> 2) & 3, b = (item >> 4) & 7, dir = item >> 7;
;     const int ch = (dir * 8 + b) * 4 + h;
;     const bf16_t* QE = (const bf16_t*)(P.ws + WS_QE); const bf16_t* KE = (const bf16_t*)(P.ws + WS_KE); const bf16_t* KDT = (const bf16_t*)(P.ws + WS_KDT);
;     const float* DEC = (const float*)(P.ws + WS_DEC); const bf16_t* VT = (const bf16_t*)(P.ws + WS_VT) + ((size_t)((b * 4 + h) * 256 + es * 64)) * KVLEN;
;     float* od = (float*)(P.ws + WS_X) + (size_t)dir * NTOK * 1024;
;     LAS unsigned char* Al = lds;
;     LAS unsigned char* ST0 = lds + 9216; LAS unsigned char* ST1 = ST0 + 17408;
;     LAS unsigned char* Lq = lds + 44032;
;     LAS unsigned char* Lk = Lq + 17408;
;     LAS unsigned char* Ld = Lk + 17408;
;     LAS unsigned char* Lv = Ld + 18432;
;     for (int i = tid; i < 17408 / 4; i += 512) ((LAS unsigned*)ST0)[i] = 0u;
;     f32x4 sreg[4];
; #pragma unroll
;     for (int eb = 0; eb < 4; ++eb) sreg[eb] = (f32x4){0.f, 0.f, 0.f, 0.f};
;     const int cbk = wave >> 1, hb = (wave & 1) * 2;
;     const int qrow = tid >> 4, qseg = tid & 15, drow = tid >> 3, dseg = tid & 7;
;     u32x4 rq[2], rk[2], rd[2], rv; f32x4 decn;
; __global__ void __launch_bounds__(512, 2) mega(Params P) {
;     ...
;         for (int it = blockIdx.x; it < 256; it += gridDim.x) gla_scan_item(P, it, lds);
.LBB0_553:
	s_cmp_eq_u32 s100, 2
	s_cbranch_scc1 .LBB0_571
	v_and_b32_e32 v181, 7, v224
	s_cmpk_gt_i32 s22, 0xff
	s_cbranch_scc1 .Lp4_gla_end
	v_lshrrev_b32_e32 v5, 3, v224
	v_mul_u32_u24_e32 v6, 0x900, v5
	v_mov_b32_e32 v55, 0
	v_lshlrev_b32_e32 v54, 1, v6
	v_lshl_add_u64 v[6:7], s[50:51], 0, v[54:55]
	s_mov_b64 s[0:1], 0x2bd18000
	v_lshl_add_u64 v[56:57], v[6:7], 0, s[0:1]
	v_lshlrev_b32_e32 v6, 4, v181
	v_mov_b32_e32 v7, v55
	s_add_u32 s44, s50, 0x2e118000
	v_lshl_add_u64 v[8:9], s[50:51], 0, v[6:7]
	s_mov_b64 s[0:1], 0x15818000
	s_addc_u32 s45, s51, 0
	v_lshl_add_u64 v[60:61], v[8:9], 0, s[0:1]
	s_add_i32 s0, 0, 0x13400
	s_add_i32 s1, 0, 0x17c00
	s_waitcnt lgkmcnt(0)
	v_bfe_u32 v3, v224, 4, 2
	v_and_b32_e32 v52, 15, v224
	s_movk_i32 s20, 0x90
	v_mov_b32_e32 v7, s0
	v_mov_b32_e32 v8, s1
	v_lshrrev_b32_e32 v1, 4, v224
	v_lshlrev_b32_e32 v2, 6, v5
	v_mad_u32_u24 v7, v5, s20, v7
	v_mad_u32_u24 v5, v5, s20, v8
	v_lshlrev_b32_e32 v62, 4, v3
	v_lshlrev_b32_e32 v8, 4, v52
	v_mov_b32_e32 v9, v55
	v_sub_u32_e32 v17, 0x10ff, v224
	v_add_u32_e32 v4, 0x1000, v2
	v_mov_b32_e32 v63, v55
	v_add_u32_e32 v59, s0, v62
	v_lshl_add_u64 v[10:11], s[50:51], 0, v[8:9]
	s_movk_i32 s21, 0x110
	s_add_i32 s0, 0, 0xf000
	v_lshrrev_b32_e32 v66, 9, v17
	v_lshlrev_b32_e32 v54, 8, v1
	v_lshlrev_b32_e32 v0, 3, v181
	v_lshlrev_b32_e32 v58, 2, v3
	s_mov_b32 s57, 0
	v_add_u32_e32 v14, 0x2400, v7
	v_lshl_add_u64 v[64:65], s[44:45], 0, v[62:63]
	v_add_u32_e32 v63, s1, v62
	v_lshl_add_u64 v[12:13], s[34:35], 0, v[8:9]
	v_mul_u32_u24_e32 v3, 0x110, v1
	v_add_u32_e32 v9, s0, v8
	v_mad_u32_u24 v15, v1, s21, 0
	v_mul_u32_u24_e32 v16, 0x90, v52
	v_add_u32_e32 v17, 2, v66
	v_lshl_add_u64 v[10:11], v[10:11], 0, v[54:55]
	s_mov_b64 s[0:1], 0x29918000
	v_lshl_add_u32 v1, v224, 2, 0
	v_lshlrev_b32_e32 v74, 1, v4
	s_mov_b32 s55, 1
	v_add_u32_e32 v67, 0, v62
	s_waitcnt vmcnt(11)
	v_or_b32_e32 v86, 0xffffff00, v58
	v_mul_u32_u24_e32 v87, 0x110, v52
	s_waitcnt vmcnt(8)
	v_and_b32_e32 v88, 30, v17
	v_mov_b32_e32 v53, v66
	v_or_b32_e32 v89, 16, v52
	v_lshl_add_u64 v[68:69], v[10:11], 0, s[0:1]
	v_lshl_add_u64 v[70:71], v[12:13], 0, v[54:55]
	v_add_u32_e32 v90, 0x2400, v1
	s_mov_b32 s54, s57
	v_lshlrev_b32_e32 v91, 2, v58
	v_lshlrev_b32_e32 v72, 1, v0
	v_mov_b32_e32 v73, v55
	v_lshlrev_b32_e32 v54, 1, v2
	s_movk_i32 s28, 0x2000
	s_movk_i32 s29, 0x6800
	s_movk_i32 s30, 0x8c0
	v_mov_b32_e32 v76, v74
	v_mov_b32_e32 v77, v55
	v_add_u32_e32 v92, v7, v6
	v_add_u32_e32 v93, v14, v6
	v_add_u32_e32 v94, v5, v6
	v_lshlrev_b32_e32 v78, 2, v52
	v_mov_b32_e32 v79, v55
	v_add_u32_e32 v95, v63, v16
	v_add_u32_e32 v96, v15, v8
	v_add_u32_e32 v97, v9, v3
	s_mov_b32 s31, s22
	s_branch .LBB0_556

; __global__ void __launch_bounds__(512, 2) mega(Params P) {
;     ...
;         for (int it = blockIdx.x; it < 512; it += gridDim.x) attn_item(P, it, lds, mfix2);
;         for (int it = blockIdx.x; it < 256; it += gridDim.x) gla_scan_item(P, it, lds);
.Lp4_gla_end:
	s_cmp_lg_u32 s100, 1
	s_cbranch_scc1 .LBB0_571
	s_mov_b32 s100, 2
	s_branch .Lp4_att
